# v146 + attention loop: single merged s_waitcnt before each half-step barrier
# baseline (speedup 1.0000x reference)
.LBB0_395:
	v_cndmask_b32_e64 v226, v178, v182, s[6:7]
	v_mul_f32_e32 v178, 0xbe0293ee, v226
	v_fmamk_f32 v50, v50, 0x3e0293ee, v178
	v_fmamk_f32 v51, v51, 0x3e0293ee, v178
	v_fmamk_f32 v52, v52, 0x3e0293ee, v178
	v_fmamk_f32 v53, v53, 0x3e0293ee, v178
	v_fmamk_f32 v54, v54, 0x3e0293ee, v178
	v_fmamk_f32 v55, v55, 0x3e0293ee, v178
	v_fmamk_f32 v56, v56, 0x3e0293ee, v178
	v_fmamk_f32 v57, v57, 0x3e0293ee, v178
	v_fmamk_f32 v58, v58, 0x3e0293ee, v178
	v_fmamk_f32 v59, v59, 0x3e0293ee, v178
	v_fmamk_f32 v60, v60, 0x3e0293ee, v178
	v_fmamk_f32 v61, v61, 0x3e0293ee, v178
	v_fmamk_f32 v62, v62, 0x3e0293ee, v178
	v_fmamk_f32 v63, v63, 0x3e0293ee, v178
	v_fmamk_f32 v64, v64, 0x3e0293ee, v178
	v_fmamk_f32 v65, v65, 0x3e0293ee, v178
	v_exp_f32_e32 v50, v50
	v_exp_f32_e32 v51, v51
	v_exp_f32_e32 v52, v52
	v_exp_f32_e32 v53, v53
	v_exp_f32_e32 v54, v54
	v_exp_f32_e32 v55, v55
	v_exp_f32_e32 v56, v56
	v_exp_f32_e32 v57, v57
	v_exp_f32_e32 v58, v58
	v_exp_f32_e32 v59, v59
	v_exp_f32_e32 v60, v60
	v_exp_f32_e32 v61, v61
	v_exp_f32_e32 v62, v62
	v_exp_f32_e32 v63, v63
	v_exp_f32_e32 v64, v64
	v_exp_f32_e32 v65, v65
	v_fmamk_f32 v82, v82, 0x3e0293ee, v178
	v_fmamk_f32 v83, v83, 0x3e0293ee, v178
	v_fmamk_f32 v84, v84, 0x3e0293ee, v178
	v_fmamk_f32 v85, v85, 0x3e0293ee, v178
	v_fmamk_f32 v86, v86, 0x3e0293ee, v178
	v_fmamk_f32 v87, v87, 0x3e0293ee, v178
	v_fmamk_f32 v88, v88, 0x3e0293ee, v178
	v_fmamk_f32 v89, v89, 0x3e0293ee, v178
	v_fmamk_f32 v90, v90, 0x3e0293ee, v178
	v_fmamk_f32 v91, v91, 0x3e0293ee, v178
	v_fmamk_f32 v92, v92, 0x3e0293ee, v178
	v_fmamk_f32 v93, v93, 0x3e0293ee, v178
	v_fmamk_f32 v94, v94, 0x3e0293ee, v178
	v_fmamk_f32 v95, v95, 0x3e0293ee, v178
	v_fmamk_f32 v96, v96, 0x3e0293ee, v178
	v_fmac_f32_e32 v178, 0x3e0293ee, v97
	s_waitcnt vmcnt(0) lgkmcnt(0)
	s_barrier
	ds_read_b128 v[230:233], v214 offset:32768
	ds_read_b128 v[234:237], v214 offset:40960
	ds_read_b128 v[238:241], v215 offset:32768
	ds_read_b128 v[242:245], v215 offset:40960
	ds_read_b128 v[180:183], v216 offset:32768
	ds_read_b128 v[184:187], v216 offset:40960
	ds_read_b128 v[246:249], v217 offset:32768
	ds_read_b128 v[250:253], v217 offset:40960
	v_exp_f32_e32 v97, v178
	v_add_f32_e32 v178, 0, v50
	v_add_f32_e32 v178, v51, v178
	s_waitcnt lgkmcnt(7)
	v_mfma_f32_32x32x16_bf16 v[114:129], v[230:233], v[158:161], v[114:129]
	v_add_f32_e32 v178, v52, v178
	v_add_f32_e32 v178, v53, v178
	v_add_f32_e32 v178, v54, v178
	v_add_f32_e32 v178, v55, v178
	v_add_f32_e32 v178, v56, v178
	v_add_f32_e32 v178, v57, v178
	v_add_f32_e32 v178, v58, v178
	s_waitcnt lgkmcnt(6)
	v_mfma_f32_32x32x16_bf16 v[98:113], v[234:237], v[158:161], v[98:113]
	ds_read_b128 v[230:233], v196 offset:32768
	ds_read_b128 v[234:237], v196 offset:40960
	v_add_f32_e32 v178, v59, v178
	v_add_f32_e32 v178, v60, v178
	v_add_f32_e32 v178, v61, v178
	v_exp_f32_e32 v82, v82
	v_add_f32_e32 v178, v62, v178
	v_exp_f32_e32 v83, v83
	s_waitcnt lgkmcnt(7)
	v_mfma_f32_32x32x16_bf16 v[114:129], v[238:241], v[154:157], v[114:129]
	v_add_f32_e32 v178, v63, v178
	v_exp_f32_e32 v84, v84
	v_add_f32_e32 v178, v64, v178
	v_exp_f32_e32 v85, v85
	v_add_f32_e32 v178, v65, v178
	v_exp_f32_e32 v86, v86
	v_add_f32_e32 v178, v82, v178
	s_waitcnt lgkmcnt(6)
	v_mfma_f32_32x32x16_bf16 v[98:113], v[242:245], v[154:157], v[98:113]
	ds_read_b128 v[238:241], v197 offset:32768
	ds_read_b128 v[242:245], v197 offset:40960
	v_exp_f32_e32 v87, v87
	v_add_f32_e32 v178, v83, v178
	v_exp_f32_e32 v88, v88
	v_add_f32_e32 v178, v84, v178
	v_exp_f32_e32 v89, v89
	v_add_f32_e32 v178, v85, v178
	s_waitcnt lgkmcnt(7)
	v_mfma_f32_32x32x16_bf16 v[114:129], v[180:183], v[150:153], v[114:129]
	v_exp_f32_e32 v90, v90
	v_add_f32_e32 v178, v86, v178
	v_exp_f32_e32 v91, v91
	v_add_f32_e32 v178, v87, v178
	v_exp_f32_e32 v92, v92
	v_add_f32_e32 v178, v88, v178
	v_exp_f32_e32 v93, v93
	s_waitcnt lgkmcnt(6)
	v_mfma_f32_32x32x16_bf16 v[98:113], v[184:187], v[150:153], v[98:113]
	ds_read_b128 v[180:183], v198 offset:32768
	ds_read_b128 v[184:187], v198 offset:40960
	v_add_f32_e32 v178, v89, v178
	v_exp_f32_e32 v94, v94
	v_add_f32_e32 v178, v90, v178
	v_exp_f32_e32 v95, v95
	v_add_f32_e32 v178, v91, v178
	v_exp_f32_e32 v96, v96
	s_waitcnt lgkmcnt(7)
	v_mfma_f32_32x32x16_bf16 v[114:129], v[246:249], v[146:149], v[114:129]
	v_add_f32_e32 v178, v92, v178
	v_add_f32_e32 v178, v93, v178
	v_add_f32_e32 v178, v94, v178
	v_add_f32_e32 v178, v95, v178
	v_add_f32_e32 v178, v96, v178
	v_add_f32_e32 v227, v97, v178
	v_mov_b32_e32 v228, v227
	s_waitcnt lgkmcnt(6)
	v_mfma_f32_32x32x16_bf16 v[98:113], v[250:253], v[146:149], v[98:113]
	ds_read_b128 v[246:249], v199 offset:32768
	ds_read_b128 v[250:253], v199 offset:40960
	v_permlane32_swap_b32_e32 v227, v228
	s_waitcnt lgkmcnt(7)
	v_mfma_f32_32x32x16_bf16 v[114:129], v[230:233], v[142:145], v[114:129]
	s_waitcnt lgkmcnt(6)
	v_mfma_f32_32x32x16_bf16 v[98:113], v[234:237], v[142:145], v[98:113]
	s_waitcnt lgkmcnt(5)
	v_mfma_f32_32x32x16_bf16 v[114:129], v[238:241], v[138:141], v[114:129]
	s_waitcnt lgkmcnt(4)
	v_mfma_f32_32x32x16_bf16 v[98:113], v[242:245], v[138:141], v[98:113]
	s_waitcnt lgkmcnt(3)
	v_mfma_f32_32x32x16_bf16 v[114:129], v[180:183], v[134:137], v[114:129]
	s_waitcnt lgkmcnt(2)
	v_mfma_f32_32x32x16_bf16 v[98:113], v[184:187], v[134:137], v[98:113]
	v_cvt_pk_bf16_f32 v178, v50, v51
	v_cvt_pk_bf16_f32 v179, v52, v53
	s_waitcnt lgkmcnt(1)
	v_mfma_f32_32x32x16_bf16 v[114:129], v[246:249], v[130:133], v[114:129]
	v_cvt_pk_bf16_f32 v180, v54, v55
	v_cvt_pk_bf16_f32 v181, v56, v57
	v_cvt_pk_bf16_f32 v182, v58, v59
	v_cvt_pk_bf16_f32 v183, v60, v61
	s_nop 0
	v_permlane32_swap_b32_e32 v178, v180
	s_waitcnt lgkmcnt(0)
	v_mfma_f32_32x32x16_bf16 v[98:113], v[250:253], v[130:133], v[98:113]
	v_cvt_pk_bf16_f32 v184, v62, v63
	v_cvt_pk_bf16_f32 v185, v64, v65
	v_cvt_pk_bf16_f32 v186, v82, v83
	v_cvt_pk_bf16_f32 v187, v84, v85
	v_cvt_pk_bf16_f32 v188, v86, v87
	v_cvt_pk_bf16_f32 v189, v88, v89
	v_cvt_pk_bf16_f32 v190, v90, v91
	v_cvt_pk_bf16_f32 v191, v92, v93
	v_cvt_pk_bf16_f32 v192, v94, v95
	v_cvt_pk_bf16_f32 v193, v96, v97
	v_permlane32_swap_b32_e32 v179, v181
	v_permlane32_swap_b32_e32 v182, v184
	v_permlane32_swap_b32_e32 v183, v185
	v_permlane32_swap_b32_e32 v186, v188
	v_permlane32_swap_b32_e32 v187, v189
	v_permlane32_swap_b32_e32 v190, v192
	v_permlane32_swap_b32_e32 v191, v193
	s_add_i32 m0, s32, 0x0
	v_add_u32_e32 v229, 0x80, v218
	global_load_lds_dwordx4 v218, s[100:101]
	s_add_i32 m0, s32, 0x400
	s_nop 0
	global_load_lds_dwordx4 v229, s[100:101]
	s_sub_u32 s100, s100, 0x4000
	s_subb_u32 s101, s101, 0
	s_add_i32 s6, s33, 1
	s_cmp_lt_i32 s6, s27
	s_cselect_b64 s[54:55], -1, 0
	s_cmp_ge_i32 s6, s27
	s_cbranch_scc1 .LBB0_397
	global_load_dwordx4 v[50:53], v221, s[52:53]
	global_load_dwordx4 v[54:57], v221, s[52:53] offset:32
	global_load_dwordx4 v[82:85], v221, s[52:53] offset:128
	global_load_dwordx4 v[86:89], v221, s[52:53] offset:160
	global_load_dwordx4 v[58:61], v221, s[52:53] offset:64
	global_load_dwordx4 v[62:65], v221, s[52:53] offset:96
	global_load_dwordx4 v[90:93], v221, s[52:53] offset:192
	global_load_dwordx4 v[94:97], v221, s[52:53] offset:224
	s_add_i32 m0, s32, 0xc000
	v_xor_b32_e32 v229, 64, v219
	global_load_lds_dwordx4 v219, s[98:99]
	s_add_i32 m0, s32, 0xc400
	v_add_u32_e32 v229, 0x400, v229
	global_load_lds_dwordx4 v229, s[98:99]
	s_sub_u32 s98, s98, 0x4000
	s_subb_u32 s99, s99, 0

.LBB0_405:
	v_cndmask_b32_e64 v182, v162, v226, s[6:7]
	v_mul_f32_e32 v180, 0xbe0293ee, v182
	v_mov_b32_e32 v183, v180
	v_fmamk_f32 v162, v114, 0x3e0293ee, v180
	v_fmamk_f32 v163, v115, 0x3e0293ee, v180
	v_fmamk_f32 v164, v116, 0x3e0293ee, v180
	v_fmamk_f32 v165, v117, 0x3e0293ee, v180
	v_fmamk_f32 v166, v118, 0x3e0293ee, v180
	v_fmamk_f32 v167, v119, 0x3e0293ee, v180
	v_fmamk_f32 v168, v120, 0x3e0293ee, v180
	v_fmamk_f32 v169, v121, 0x3e0293ee, v180
	v_fmamk_f32 v179, v122, 0x3e0293ee, v180
	v_fmamk_f32 v181, v123, 0x3e0293ee, v180
	v_fmamk_f32 v124, v124, 0x3e0293ee, v180
	v_fmamk_f32 v125, v125, 0x3e0293ee, v180
	v_fmamk_f32 v126, v126, 0x3e0293ee, v180
	v_fmamk_f32 v127, v127, 0x3e0293ee, v180
	v_fmamk_f32 v128, v128, 0x3e0293ee, v180
	v_fmac_f32_e32 v183, 0x3e0293ee, v129
	v_exp_f32_e32 v175, v162
	v_exp_f32_e32 v177, v163
	v_exp_f32_e32 v173, v164
	v_exp_f32_e32 v176, v165
	v_exp_f32_e32 v171, v166
	v_exp_f32_e32 v174, v167
	v_exp_f32_e32 v170, v168
	v_exp_f32_e32 v172, v169
	v_exp_f32_e32 v164, v179
	v_exp_f32_e32 v167, v181
	v_exp_f32_e32 v163, v124
	v_exp_f32_e32 v165, v125
	v_exp_f32_e32 v162, v126
	v_exp_f32_e32 v169, v127
	v_exp_f32_e32 v166, v128
	v_exp_f32_e32 v168, v183
	v_pk_fma_f32 v[128:129], v[98:99], s[16:17], v[180:181] op_sel_hi:[1,0,0]
	v_add_f32_e32 v98, v223, v224
	v_fmac_f32_e32 v98, v220, v213
	v_add_f32_e32 v213, v227, v228
	s_addk_i32 s38, 0xff80
	s_add_i32 s33, s33, 2
	v_pk_fma_f32 v[114:115], v[112:113], s[16:17], v[180:181] op_sel_hi:[1,0,0]
	v_pk_fma_f32 v[116:117], v[110:111], s[16:17], v[180:181] op_sel_hi:[1,0,0]
	v_pk_fma_f32 v[118:119], v[108:109], s[16:17], v[180:181] op_sel_hi:[1,0,0]
	v_pk_fma_f32 v[120:121], v[106:107], s[16:17], v[180:181] op_sel_hi:[1,0,0]
	v_pk_fma_f32 v[122:123], v[104:105], s[16:17], v[180:181] op_sel_hi:[1,0,0]
	v_pk_fma_f32 v[124:125], v[102:103], s[16:17], v[180:181] op_sel_hi:[1,0,0]
	v_pk_fma_f32 v[126:127], v[100:101], s[16:17], v[180:181] op_sel_hi:[1,0,0]
	v_fmac_f32_e32 v213, v98, v225
	v_add_u32_e32 v221, 0xfffffe00, v221
	s_cmp_ge_i32 s33, s27
	v_add_u32_e32 v222, 0x80, v222
	s_waitcnt vmcnt(0) lgkmcnt(0)
	s_barrier
	s_cbranch_scc1 .LBB0_408
	v_mov_b32_e32 v220, v178
	s_branch .LBB0_389
